# v72 + FoX step loop: the two per-tile early-exit decay reads of a step fetched with one ds_read2_b32 (one LDS round trip less per step)
# baseline (speedup 1.0000x reference)
; template <bool MOBA>
; __device__ __forceinline__ void attn_unit(unsigned char* lds, LAS unsigned char* lds3, const Params& p, int b, int h, int qb) {
;     ...
;         const int it = 2 * st + sub, t = NT - 1 - it, slot = buf * 2 + sub;
;         const int tl = t - 4 * qb;
;         if (!MOBA && !wdone && (fq0 - Fs[64 * t + 63]) < -141.f) wdone = true;
;         bool active = (tl <= (w >> 1)) && !wdone;
.LBB0_536:
	s_xor_b64 vcc, s[6:7], -1
	s_mov_b64 s[6:7], -1
	s_andn2_b64 vcc, exec, vcc
	v_add_u32_e32 v138, s5, v134
	s_cbranch_vccnz .LBB0_539
	v_add_u32_e32 v1, 0x122fc, v138
	ds_read2_b32 v[240:241], v1 offset1:64
	s_mov_b32 s6, 0xc30d0000
	s_waitcnt lgkmcnt(0)
	v_sub_f32_e32 v1, v119, v241
	v_cmp_ngt_f32_e32 vcc, s6, v1
	s_mov_b64 s[6:7], 0
	s_cbranch_vccnz .LBB0_539
	s_mov_b64 s[6:7], -1

; template <bool MOBA>
; __device__ __forceinline__ void attn_unit(unsigned char* lds, LAS unsigned char* lds3, const Params& p, int b, int h, int qb) {
;     ...
;         const int it = 2 * st + sub, t = NT - 1 - it, slot = buf * 2 + sub;
;         const int tl = t - 4 * qb;
;         if (!MOBA && !wdone && (fq0 - Fs[64 * t + 63]) < -141.f) wdone = true;
;         bool active = (tl <= (w >> 1)) && !wdone;
.LBB0_543:
	s_xor_b64 s[6:7], s[6:7], -1
	s_andn2_b64 vcc, exec, s[6:7]
	s_mov_b64 s[6:7], -1
	s_cbranch_vccnz .LBB0_546
	s_mov_b32 s6, 0xc30d0000
	s_waitcnt lgkmcnt(0)
	v_sub_f32_e32 v74, v119, v240
	v_cmp_ngt_f32_e32 vcc, s6, v74
	s_mov_b64 s[6:7], 0
	s_cbranch_vccnz .LBB0_546
	s_mov_b64 s[6:7], -1
